# v17 + split grid barrier between projection and attention: XCDs released locally, cross-XCD completion awaited before the first NSA unit (guarded)
# speedup vs baseline: 1.0306x; 1.0086x over previous
; __device__ __forceinline__ unsigned xb_ld(unsigned* p)              { return __hip_atomic_load(p, __ATOMIC_RELAXED, __HIP_MEMORY_SCOPE_AGENT); }
; __device__ __forceinline__ unsigned xb_add(unsigned* p, unsigned v) { return __hip_atomic_fetch_add(p, v, __ATOMIC_RELAXED, __HIP_MEMORY_SCOPE_AGENT); }
; #define XB_SPIN(cond, bar) do { unsigned _sp = 0; while (cond) { __builtin_amdgcn_s_sleep(1); \
;     if ((++_sp & 255u) == 0u) { if (xb_ld(&(bar)[XB_TMO])) break; if (_sp > XB_SPIN_CAP) { atomicAdd(&(bar)[XB_TMO], 1u); break; } } } } while (0)
; __device__ __forceinline__ void xcd_barrier(const XcdBarrier& b, int tid) {
;     ...
;         if (old + 1u == (gen + 1u) * nloc) {
;             __builtin_amdgcn_fence(__ATOMIC_RELEASE, "agent");
;             asm volatile("s_waitcnt vmcnt(0)" ::: "memory");
;             const unsigned og = xb_add(&bar[XB_TOP], 1u);
;             const unsigned tg = og / nx;
;             if (og + 1u == (tg + 1u) * nx) xb_add(&bar[XB_TOPGEN], 1u);
;             else XB_SPIN(xb_ld(&bar[XB_TOPGEN]) == tg, bar);
;             __builtin_amdgcn_fence(__ATOMIC_ACQUIRE, "agent");
;             xb_add(&bar[XB_XGEN(b.x)], 1u);
.LBB0_724:
	s_or_b64 exec, exec, s[10:11]
	v_cvt_f32_u32_e32 v3, v0
	s_waitcnt vmcnt(0)
	v_readfirstlane_b32 s0, v2
	s_add_u32 s10, s40, 0x3500
	s_addc_u32 s11, s41, 0
	v_rcp_iflag_f32_e32 v3, v3
	v_add_u32_e32 v1, s0, v1
	v_add_u32_e32 v4, 1, v1
	s_mov_b64 s[12:13], -1
	v_mul_f32_e32 v2, 0x4f7ffffe, v3
	v_cvt_u32_f32_e32 v2, v2
	v_sub_u32_e32 v3, 0, v0
	v_mul_lo_u32 v3, v3, v2
	v_mul_hi_u32 v3, v2, v3
	v_add_u32_e32 v2, v2, v3
	v_mul_hi_u32 v2, v1, v2
	v_mul_lo_u32 v3, v2, v0
	v_sub_u32_e32 v1, v1, v3
	v_add_u32_e32 v5, 1, v2
	v_cmp_ge_u32_e32 vcc, v1, v0
	v_sub_u32_e32 v3, v1, v0
	s_nop 0
	v_cndmask_b32_e32 v2, v2, v5, vcc
	v_cndmask_b32_e32 v1, v1, v3, vcc
	v_add_u32_e32 v3, 1, v2
	v_cmp_ge_u32_e32 vcc, v1, v0
	s_nop 1
	v_cndmask_b32_e32 v2, v2, v3, vcc
	v_mul_lo_u32 v1, v0, v2
	v_add_u32_e32 v0, v1, v0
	v_cmp_ne_u32_e32 vcc, v4, v0
	v_mov_b64_e32 v[0:1], s[10:11]
	s_and_saveexec_b64 s[8:9], vcc
	s_cbranch_execz .LBB0_736
	v_readlane_b32 s0, v248, 32
	s_nop 3
	s_cmp_eq_u32 s0, 1
	s_cbranch_scc0 .Lsplit3_spin
	s_mov_b64 s[12:13], 0
	s_branch .LBB0_736
.Lsplit3_spin:
	v_mov_b32_e32 v0, 0
	global_load_dword v1, v0, s[10:11] sc1
	s_mov_b64 s[16:17], 0
	s_waitcnt vmcnt(0)
	v_cmp_eq_u32_e32 vcc, v1, v2
	s_and_saveexec_b64 s[14:15], vcc
	s_cbranch_execz .LBB0_735
	s_add_u32 s12, s40, 0x200
	s_addc_u32 s13, s41, 0
	s_mov_b32 s0, 1
	s_branch .LBB0_728

; #define LAS __attribute__((address_space(3)))
; __global__ void __launch_bounds__(NTHREADS, 2) fwd_kernel(Args a) {
;     ...
;         int nxt = 0; if (tid == 0) nxt = (int)__hip_atomic_fetch_add((unsigned*)(ws + NSA_Q_OFF), 1u, __ATOMIC_RELAXED, __HIP_MEMORY_SCOPE_AGENT);
;         __syncthreads();
;         { const float* TAB = (const float*)(ws + WS_TAB); LAS float* tl = (LAS float*)(lds + NL_TAB); for (int i = tid; i < 8 * 320; i += NTHREADS) { const int hd = i / 320, d = i % 320 - 64; tl[i] = (d < 0) ? NEG : TAB[hd * 128 + min(d, 127)]; } }
;         __syncthreads();
;         if (tid < 32) { unsigned sp = 0; while (__hip_atomic_load((unsigned*)(ws + CMP_CNT_OFF) + 64 * tid, __ATOMIC_RELAXED, __HIP_MEMORY_SCOPE_AGENT) < 8u) { __builtin_amdgcn_s_sleep(2); if (++sp > (1u << 22)) break; } }
.LBB0_864:
	s_or_b64 exec, exec, s[6:7]
	s_waitcnt vmcnt(0) lgkmcnt(0)
	v_readfirstlane_b32 s1, v1
	s_nop 1
	v_add_u32_e32 v168, s1, v0
	v_readlane_b32 s6, v248, 32
	s_nop 3
	s_cmp_eq_u32 s6, 1
	s_cbranch_scc0 .Lgw_done
	v_mov_b32_e32 v1, 0x3500
	s_mov_b32 s6, 0
.Lgw_loop:
	global_load_dword v2, v1, s[40:41] sc1
	s_waitcnt vmcnt(0)
	v_cmp_gt_u32_e32 vcc, 2, v2
	s_cbranch_vccz .Lgw_ok
	s_sleep 1
	s_add_i32 s6, s6, 1
	s_cmp_lt_u32 s6, 0x40000
	s_cbranch_scc1 .Lgw_loop
.Lgw_ok:
	buffer_inv sc1
	s_waitcnt vmcnt(0)
.Lgw_done:
.LBB0_865:
	s_or_b64 exec, exec, s[4:5]
	s_movk_i32 s1, 0xa00
	v_cmp_gt_i32_e32 vcc, s1, v214
	s_waitcnt vmcnt(0) lgkmcnt(0)
	s_barrier
	s_and_saveexec_b64 s[4:5], vcc
	s_cbranch_execz .LBB0_870
	s_add_u32 s6, s40, 0x3220000
	v_lshl_add_u32 v0, v214, 2, 0
	s_addc_u32 s7, s41, 0
	v_add_u32_e32 v0, 0x1d600, v0
	s_mov_b64 s[8:9], 0
	s_mov_b32 s1, 0x66666667
	s_movk_i32 s12, 0x7ff
	v_mov_b32_e32 v1, v214
	s_branch .LBB0_868
